# v11 + K2 tile DMA issued right after K1 in the attention unit prologue
# baseline (speedup 1.0000x reference)
.LBB0_556:
	s_or_b64 exec, exec, s[60:61]
	s_add_u32 s98, s64, 0x48000
	s_addc_u32 s99, s65, 0
	s_add_i32 m0, s73, 0x6000
	s_nop 0
	global_load_lds_dwordx4 v183, s[98:99]
	s_and_saveexec_b64 s[100:101], s[2:3]
	s_add_u32 s98, s46, 0x2000
	s_addc_u32 s99, s47, 0
	s_add_i32 m0, s76, 0x6000
	s_nop 0
	global_load_lds_dwordx4 v184, s[98:99]
	s_or_b64 exec, exec, s[100:101]
	s_lshl_b64 s[60:61], s[56:57], 18
	v_readlane_b32 s1, v246, 39
	s_add_u32 s1, s1, s44
	v_readlane_b32 s44, v246, 40
	s_addc_u32 s44, s44, s45
	s_add_u32 s1, s1, s48
	s_addc_u32 s48, s44, s49
	s_lshl_b64 s[44:45], s[60:61], 2
	v_readlane_b32 s49, v246, 51
	s_add_u32 s44, s49, s44
	v_readlane_b32 s49, v246, 52
	s_addc_u32 s45, s49, s45
	s_lshl_b32 s81, s62, 8
	s_add_i32 s52, s81, s71
	v_or_b32_e32 v0, s52, v170
	v_mov_b32_e32 v1, v153
	v_lshlrev_b64 v[0:1], 7, v[0:1]
	v_lshl_add_u64 v[0:1], s[44:45], 0, v[0:1]
	v_lshl_add_u64 v[12:13], v[146:147], 2, v[0:1]
	s_mul_i32 s44, s52, 0x900
	s_mov_b32 s98, s0
	s_ashr_i32 s99, s0, 31
	s_lshl_b64 s[98:99], s[98:99], 9
	s_lshl_b32 s100, s56, 7
	s_ashr_i32 s101, s100, 31
	v_lshl_add_u64 v[250:251], v[162:163], 0, s[98:99]
	v_lshl_add_u64 v[252:253], s[100:101], 2, v[164:165]
	global_load_dword v247, v[250:251], off
	global_load_dword v248, v[250:251], off offset:256
	global_load_dword v249, v[252:253], off
	global_load_dword v254, v[252:253], off offset:256
	global_load_dwordx4 v[0:3], v[12:13], off
	global_load_dwordx4 v[4:7], v[12:13], off offset:16
	s_mul_hi_u32 s45, s52, 0x900
	global_load_dwordx4 v[8:11], v[12:13], off offset:48
	s_nop 0
	global_load_dwordx4 v[12:15], v[12:13], off offset:32
	s_add_u32 s44, s1, s44
	s_addc_u32 s45, s48, s45
	v_lshl_add_u64 v[16:17], s[44:45], 0, v[152:153]
	v_lshl_add_u64 v[24:25], v[150:151], 1, v[16:17]
	global_load_dwordx4 v[16:19], v[24:25], off offset:128
	global_load_dwordx4 v[20:23], v[24:25], off offset:160
	global_load_dwordx4 v[116:119], v[24:25], off
	global_load_dwordx4 v[112:115], v[24:25], off offset:32
	global_load_dwordx4 v[104:107], v[24:25], off offset:64
	global_load_dwordx4 v[96:99], v[24:25], off offset:96
	v_readlane_b32 s44, v246, 58
	v_readlane_b32 s45, v246, 59
	s_andn2_b64 vcc, exec, s[44:45]
	s_waitcnt vmcnt(9)
	v_mov_b32_e32 v24, v0
	v_mov_b32_e32 v25, v2
	v_mov_b32_e32 v2, v1
	s_waitcnt vmcnt(8)
	v_mov_b32_e32 v0, v4
	v_mov_b32_e32 v1, v6
	v_mov_b32_e32 v6, v5
	s_waitcnt vmcnt(6)
	v_mov_b32_e32 v4, v12
	v_mov_b32_e32 v5, v14
	v_mov_b32_e32 v14, v13
	v_mov_b32_e32 v12, v8
	v_mov_b32_e32 v13, v10
	v_mov_b32_e32 v10, v9
	s_waitcnt vmcnt(5)
	v_and_b32_e32 v9, 0xffff0000, v16
	v_lshlrev_b32_e32 v8, 16, v16
	s_waitcnt vmcnt(4)
	v_and_b32_e32 v27, 0xffff0000, v20
	v_lshlrev_b32_e32 v26, 16, v20
	v_and_b32_e32 v29, 0xffff0000, v17
	v_lshlrev_b32_e32 v28, 16, v17
	v_and_b32_e32 v17, 0xffff0000, v21
	v_lshlrev_b32_e32 v16, 16, v21
	v_and_b32_e32 v21, 0xffff0000, v18
	v_lshlrev_b32_e32 v20, 16, v18
	v_and_b32_e32 v31, 0xffff0000, v22
	v_lshlrev_b32_e32 v30, 16, v22
	v_and_b32_e32 v33, 0xffff0000, v19
	v_lshlrev_b32_e32 v32, 16, v19
	v_and_b32_e32 v19, 0xffff0000, v23
	v_lshlrev_b32_e32 v18, 16, v23
	v_pk_mul_f32 v[22:23], v[2:3], v[26:27]
	v_pk_mul_f32 v[26:27], v[24:25], v[26:27]
	v_pk_mul_f32 v[34:35], v[6:7], v[16:17]
	v_pk_mul_f32 v[16:17], v[0:1], v[16:17]
	v_pk_mul_f32 v[36:37], v[14:15], v[30:31]
	v_pk_mul_f32 v[30:31], v[4:5], v[30:31]
	v_pk_mul_f32 v[38:39], v[10:11], v[18:19]
	v_pk_mul_f32 v[18:19], v[12:13], v[18:19]
	v_pk_fma_f32 v[22:23], v[24:25], v[8:9], v[22:23] neg_lo:[0,0,1] neg_hi:[0,0,1]
	v_pk_fma_f32 v[2:3], v[2:3], v[8:9], v[26:27]
	v_pk_fma_f32 v[0:1], v[0:1], v[28:29], v[34:35] neg_lo:[0,0,1] neg_hi:[0,0,1]
	v_pk_fma_f32 v[6:7], v[6:7], v[28:29], v[16:17]
	v_pk_fma_f32 v[4:5], v[4:5], v[20:21], v[36:37] neg_lo:[0,0,1] neg_hi:[0,0,1]
	v_pk_fma_f32 v[8:9], v[14:15], v[20:21], v[30:31]
	v_pk_fma_f32 v[12:13], v[12:13], v[32:33], v[38:39] neg_lo:[0,0,1] neg_hi:[0,0,1]
	v_pk_fma_f32 v[10:11], v[10:11], v[32:33], v[18:19]
	v_cvt_pk_bf16_f32 v108, v22, v23
	v_cvt_pk_bf16_f32 v109, v0, v1
	v_cvt_pk_bf16_f32 v110, v4, v5
	v_cvt_pk_bf16_f32 v111, v12, v13
	v_cvt_pk_bf16_f32 v100, v2, v3
	v_cvt_pk_bf16_f32 v101, v6, v7
	v_cvt_pk_bf16_f32 v102, v8, v9
	v_cvt_pk_bf16_f32 v103, v10, v11
	s_cbranch_vccnz .LBB0_558
	s_waitcnt vmcnt(3)
	v_lshlrev_b32_e32 v0, 16, v116
	v_fma_f32 v0, v0, v0, 0
	v_and_b32_e32 v1, 0xffff0000, v116
	v_fmac_f32_e32 v0, v1, v1
	v_lshlrev_b32_e32 v1, 16, v117
	v_fmac_f32_e32 v0, v1, v1
	v_and_b32_e32 v1, 0xffff0000, v117
	v_fmac_f32_e32 v0, v1, v1
	v_lshlrev_b32_e32 v1, 16, v118
	v_fmac_f32_e32 v0, v1, v1
	v_and_b32_e32 v1, 0xffff0000, v118
	v_fmac_f32_e32 v0, v1, v1
	v_lshlrev_b32_e32 v1, 16, v119
	v_fmac_f32_e32 v0, v1, v1
	v_and_b32_e32 v1, 0xffff0000, v119
	v_fmac_f32_e32 v0, v1, v1
	s_waitcnt vmcnt(2)
	v_lshlrev_b32_e32 v1, 16, v112
	v_fmac_f32_e32 v0, v1, v1
	v_and_b32_e32 v1, 0xffff0000, v112
	v_fmac_f32_e32 v0, v1, v1
	v_lshlrev_b32_e32 v1, 16, v113
	v_fmac_f32_e32 v0, v1, v1
	v_and_b32_e32 v1, 0xffff0000, v113
	v_fmac_f32_e32 v0, v1, v1
	v_lshlrev_b32_e32 v1, 16, v114
	v_fmac_f32_e32 v0, v1, v1
	v_and_b32_e32 v1, 0xffff0000, v114
	v_fmac_f32_e32 v0, v1, v1
	v_lshlrev_b32_e32 v1, 16, v115
	v_fmac_f32_e32 v0, v1, v1
	v_and_b32_e32 v1, 0xffff0000, v115
	v_fmac_f32_e32 v0, v1, v1
	s_waitcnt vmcnt(1)
	v_lshlrev_b32_e32 v1, 16, v104
	v_fmac_f32_e32 v0, v1, v1
	v_and_b32_e32 v1, 0xffff0000, v104
	v_fmac_f32_e32 v0, v1, v1
	v_lshlrev_b32_e32 v1, 16, v105
	v_fmac_f32_e32 v0, v1, v1
	v_and_b32_e32 v1, 0xffff0000, v105
	v_fmac_f32_e32 v0, v1, v1
	v_lshlrev_b32_e32 v1, 16, v106
	v_fmac_f32_e32 v0, v1, v1
	v_and_b32_e32 v1, 0xffff0000, v106
	v_fmac_f32_e32 v0, v1, v1
	v_lshlrev_b32_e32 v1, 16, v107
	v_fmac_f32_e32 v0, v1, v1
	v_and_b32_e32 v1, 0xffff0000, v107
	v_fmac_f32_e32 v0, v1, v1
	s_waitcnt vmcnt(0)
	v_lshlrev_b32_e32 v1, 16, v96
	v_fmac_f32_e32 v0, v1, v1
	v_and_b32_e32 v1, 0xffff0000, v96
	v_fmac_f32_e32 v0, v1, v1
	v_lshlrev_b32_e32 v1, 16, v97
	v_fmac_f32_e32 v0, v1, v1
	v_and_b32_e32 v1, 0xffff0000, v97
	v_fmac_f32_e32 v0, v1, v1
	v_lshlrev_b32_e32 v1, 16, v98
	v_fmac_f32_e32 v0, v1, v1
	v_and_b32_e32 v1, 0xffff0000, v98
	v_fmac_f32_e32 v0, v1, v1
	v_lshlrev_b32_e32 v1, 16, v99
	v_fmac_f32_e32 v0, v1, v1
	v_and_b32_e32 v1, 0xffff0000, v99
	v_fmac_f32_e32 v0, v1, v1
	v_lshlrev_b32_e32 v1, 16, v108
	v_fmac_f32_e32 v0, v1, v1
	v_and_b32_e32 v1, 0xffff0000, v108
	v_fmac_f32_e32 v0, v1, v1
	v_lshlrev_b32_e32 v1, 16, v109
	v_fmac_f32_e32 v0, v1, v1
	v_and_b32_e32 v1, 0xffff0000, v109
	v_fmac_f32_e32 v0, v1, v1
	v_lshlrev_b32_e32 v1, 16, v110
	v_fmac_f32_e32 v0, v1, v1
	v_and_b32_e32 v1, 0xffff0000, v110
	v_fmac_f32_e32 v0, v1, v1
	v_lshlrev_b32_e32 v1, 16, v111
	v_fmac_f32_e32 v0, v1, v1
	v_and_b32_e32 v1, 0xffff0000, v111
	v_fmac_f32_e32 v0, v1, v1
	v_lshlrev_b32_e32 v1, 16, v100
	v_fmac_f32_e32 v0, v1, v1
	v_and_b32_e32 v1, 0xffff0000, v100
	v_fmac_f32_e32 v0, v1, v1
	v_lshlrev_b32_e32 v1, 16, v101
	v_fmac_f32_e32 v0, v1, v1
	v_and_b32_e32 v1, 0xffff0000, v101
	v_fmac_f32_e32 v0, v1, v1
	v_lshlrev_b32_e32 v1, 16, v102
	v_fmac_f32_e32 v0, v1, v1
	v_and_b32_e32 v1, 0xffff0000, v102
	v_fmac_f32_e32 v0, v1, v1
	v_lshlrev_b32_e32 v1, 16, v103
	v_fmac_f32_e32 v0, v1, v1
	v_and_b32_e32 v1, 0xffff0000, v103
	s_ashr_i32 s1, s0, 31
	v_fmac_f32_e32 v0, v1, v1
	s_lshl_b64 s[0:1], s[0:1], 9
	s_lshl_b32 s44, s56, 7
	v_mov_b32_e32 v1, v0
	s_ashr_i32 s45, s44, 31
	s_nop 0
	v_permlane32_swap_b32_e32 v0, v1
	v_add_f32_e32 v0, v0, v1
	s_mov_b32 s0, 0x45610000
	v_max_f32_e32 v0, v0, v0
	v_max_f32_e32 v1, v247, v247
	v_max_f32_e32 v4, v248, v248
	v_max_f32_e32 v3, v249, v249
	v_max_f32_e32 v2, v254, v254
	s_nop 0
	v_max_f32_e32 v2, v3, v2
	s_nop 1
	v_max_f32_dpp v0, v0, v0 quad_perm:[1,0,3,2] row_mask:0xf bank_mask:0xf
	v_max_f32_dpp v1, v1, v1 quad_perm:[1,0,3,2] row_mask:0xf bank_mask:0xf
	v_max_f32_dpp v4, v4, v4 quad_perm:[1,0,3,2] row_mask:0xf bank_mask:0xf
	v_max_f32_dpp v2, v2, v2 quad_perm:[1,0,3,2] row_mask:0xf bank_mask:0xf
	v_max_f32_dpp v0, v0, v0 quad_perm:[2,3,0,1] row_mask:0xf bank_mask:0xf
	v_max_f32_dpp v1, v1, v1 quad_perm:[2,3,0,1] row_mask:0xf bank_mask:0xf
	v_max_f32_dpp v4, v4, v4 quad_perm:[2,3,0,1] row_mask:0xf bank_mask:0xf
	v_max_f32_dpp v2, v2, v2 quad_perm:[2,3,0,1] row_mask:0xf bank_mask:0xf
	v_max_f32_dpp v0, v0, v0 row_half_mirror row_mask:0xf bank_mask:0xf
	v_max_f32_dpp v1, v1, v1 row_half_mirror row_mask:0xf bank_mask:0xf
	v_max_f32_dpp v4, v4, v4 row_half_mirror row_mask:0xf bank_mask:0xf
	v_max_f32_dpp v2, v2, v2 row_half_mirror row_mask:0xf bank_mask:0xf
	v_max_f32_dpp v0, v0, v0 row_mirror row_mask:0xf bank_mask:0xf
	v_max_f32_dpp v1, v1, v1 row_mirror row_mask:0xf bank_mask:0xf
	v_max_f32_dpp v4, v4, v4 row_mirror row_mask:0xf bank_mask:0xf
	v_max_f32_dpp v2, v2, v2 row_mirror row_mask:0xf bank_mask:0xf
	v_max_f32_dpp v0, v0, v0 row_bcast:15 row_mask:0xa bank_mask:0xf
	v_max_f32_dpp v1, v1, v1 row_bcast:15 row_mask:0xa bank_mask:0xf
	v_max_f32_dpp v4, v4, v4 row_bcast:15 row_mask:0xa bank_mask:0xf
	v_max_f32_dpp v2, v2, v2 row_bcast:15 row_mask:0xa bank_mask:0xf
	v_max_f32_dpp v0, v0, v0 row_bcast:31 row_mask:0xc bank_mask:0xf
	v_max_f32_dpp v1, v1, v1 row_bcast:31 row_mask:0xc bank_mask:0xf
	v_max_f32_dpp v4, v4, v4 row_bcast:31 row_mask:0xc bank_mask:0xf
	v_max_f32_dpp v2, v2, v2 row_bcast:31 row_mask:0xc bank_mask:0xf
	v_add_f32_e32 v1, v1, v4
	v_add_f32_e32 v1, v2, v1
	v_mul_f32_e32 v0, v0, v1
	v_mul_f32_e32 v0, 0x3f866666, v0
	v_cmp_ge_f32_e32 vcc, s0, v0
	s_nop 1
	v_cndmask_b32_e64 v0, 0, 1, vcc
	s_nop 0
	v_readlane_b32 s0, v0, 63
	s_bitcmp1_b32 s0, 0
	s_cselect_b64 s[44:45], -1, 0
	s_branch .LBB0_559

.LBB0_559:
.LBB0_561:
	s_waitcnt vmcnt(5) lgkmcnt(0)
	s_barrier
	ds_read_b128 v[0:3], v179
	ds_read_b128 v[32:35], v179 offset:2048
	s_cmp_lg_u32 s62, 0
	s_cselect_b64 s[0:1], -1, 0
	s_and_b64 vcc, exec, s[0:1]
	s_waitcnt vmcnt(3) lgkmcnt(1)
	v_mfma_f32_32x32x16_bf16 v[16:31], v[0:3], v[116:119], 0
	ds_read_b128 v[0:3], v179 offset:512
	s_waitcnt vmcnt(2) lgkmcnt(1)
	v_mfma_f32_32x32x16_bf16 v[16:31], v[32:35], v[112:115], v[16:31]
	ds_read_b128 v[32:35], v179 offset:2560
	s_waitcnt lgkmcnt(1)
	v_mfma_f32_32x32x16_bf16 v[0:15], v[0:3], v[116:119], 0
	s_waitcnt lgkmcnt(0)
	v_mfma_f32_32x32x16_bf16 v[0:15], v[32:35], v[112:115], v[0:15]
	ds_read_b128 v[32:35], v179 offset:4096
	s_waitcnt vmcnt(1) lgkmcnt(0)
	v_mfma_f32_32x32x16_bf16 v[16:31], v[32:35], v[104:107], v[16:31]
	ds_read_b128 v[32:35], v179 offset:4608
	s_waitcnt lgkmcnt(0)
	v_mfma_f32_32x32x16_bf16 v[0:15], v[32:35], v[104:107], v[0:15]
	ds_read_b128 v[32:35], v179 offset:6144
	s_waitcnt vmcnt(0) lgkmcnt(0)
	v_mfma_f32_32x32x16_bf16 v[16:31], v[32:35], v[96:99], v[16:31]
	ds_read_b128 v[32:35], v179 offset:6656
	s_waitcnt lgkmcnt(0)
	v_mfma_f32_32x32x16_bf16 v[0:15], v[32:35], v[96:99], v[0:15]
	ds_read_b128 v[32:35], v179 offset:8192
	s_waitcnt lgkmcnt(0)
	v_mfma_f32_32x32x16_bf16 v[16:31], v[32:35], v[108:111], v[16:31]
	ds_read_b128 v[32:35], v179 offset:8704
	s_waitcnt lgkmcnt(0)
	v_mfma_f32_32x32x16_bf16 v[0:15], v[32:35], v[108:111], v[0:15]
	ds_read_b128 v[32:35], v179 offset:10240
	s_waitcnt lgkmcnt(0)
	v_mfma_f32_32x32x16_bf16 v[16:31], v[32:35], v[100:103], v[16:31]
	ds_read_b128 v[32:35], v179 offset:10752
	s_waitcnt lgkmcnt(0)
	v_mfma_f32_32x32x16_bf16 v[0:15], v[32:35], v[100:103], v[0:15]
	s_cbranch_vccnz .LBB0_563
	v_readlane_b32 s48, v246, 61
	v_readlane_b32 s49, v246, 62
	s_nop 5
	v_cndmask_b32_e64 v32, v16, v218, s[48:49]
	v_readlane_b32 s48, v246, 63
	v_readlane_b32 s49, v245, 0
	s_nop 1
	v_cndmask_b32_e64 v0, v0, v218, s[48:49]
	v_readlane_b32 s48, v245, 1
	v_readlane_b32 s49, v245, 2
	s_nop 1
	v_cndmask_b32_e64 v17, v218, v17, s[48:49]
	v_cndmask_b32_e64 v16, v32, v16, s[48:49]
	v_readlane_b32 s48, v245, 3
	v_readlane_b32 s49, v245, 4
	s_nop 1
	v_cndmask_b32_e64 v1, v1, v218, s[48:49]
	v_readlane_b32 s48, v245, 5
	v_readlane_b32 s49, v245, 6
	s_nop 1
	v_cndmask_b32_e64 v18, v18, v218, s[48:49]
	v_readlane_b32 s48, v245, 7
	v_readlane_b32 s49, v245, 8
	s_nop 1
	v_cndmask_b32_e64 v2, v2, v218, s[48:49]
	v_readlane_b32 s48, v245, 9
	v_readlane_b32 s49, v245, 10
	s_nop 1
	v_cndmask_b32_e64 v19, v19, v218, s[48:49]
	v_readlane_b32 s48, v245, 11
	v_readlane_b32 s49, v245, 12
	s_nop 1
	v_cndmask_b32_e64 v3, v3, v218, s[48:49]
	v_readlane_b32 s48, v245, 13
	v_readlane_b32 s49, v245, 14
	s_nop 1
	v_cndmask_b32_e64 v20, v20, v218, s[48:49]
	v_readlane_b32 s48, v245, 15
	v_readlane_b32 s49, v245, 16
	s_nop 1
	v_cndmask_b32_e64 v4, v4, v218, s[48:49]
	v_readlane_b32 s48, v245, 17
	v_readlane_b32 s49, v245, 18
	s_nop 1
	v_cndmask_b32_e64 v21, v21, v218, s[48:49]
	v_readlane_b32 s48, v245, 19
	v_readlane_b32 s49, v245, 20
	s_nop 1
	v_cndmask_b32_e64 v5, v5, v218, s[48:49]
	v_readlane_b32 s48, v245, 21
	v_readlane_b32 s49, v245, 22
	s_nop 1
	v_cndmask_b32_e64 v22, v22, v218, s[48:49]
	v_readlane_b32 s48, v245, 23
	v_readlane_b32 s49, v245, 24
	s_nop 1
	v_cndmask_b32_e64 v6, v6, v218, s[48:49]
	v_readlane_b32 s48, v245, 25
	v_readlane_b32 s49, v245, 26
	s_nop 1
	v_cndmask_b32_e64 v23, v23, v218, s[48:49]
	v_readlane_b32 s48, v245, 27
	v_readlane_b32 s49, v245, 28
	s_nop 1
	v_cndmask_b32_e64 v7, v7, v218, s[48:49]
	v_readlane_b32 s48, v245, 29
	v_readlane_b32 s49, v245, 30
	s_nop 1
	v_cndmask_b32_e64 v24, v24, v218, s[48:49]
	v_readlane_b32 s48, v245, 31
	v_readlane_b32 s49, v245, 32
	s_nop 1
	v_cndmask_b32_e64 v8, v8, v218, s[48:49]
	v_readlane_b32 s48, v245, 33
	v_readlane_b32 s49, v245, 34
	s_nop 1
	v_cndmask_b32_e64 v25, v25, v218, s[48:49]
	v_readlane_b32 s48, v245, 35
	v_readlane_b32 s49, v245, 36
	s_nop 1
	v_cndmask_b32_e64 v9, v9, v218, s[48:49]
	v_readlane_b32 s48, v245, 37
	v_readlane_b32 s49, v245, 38
	s_nop 1
	v_cndmask_b32_e64 v26, v26, v218, s[48:49]
	v_readlane_b32 s48, v245, 39
	v_readlane_b32 s49, v245, 40
	s_nop 1
	v_cndmask_b32_e64 v10, v10, v218, s[48:49]
	v_readlane_b32 s48, v245, 41
	v_readlane_b32 s49, v245, 42
	s_nop 1
	v_cndmask_b32_e64 v27, v27, v218, s[48:49]
	v_readlane_b32 s48, v245, 43
	v_readlane_b32 s49, v245, 44
	s_nop 1
	v_cndmask_b32_e64 v11, v11, v218, s[48:49]
	v_readlane_b32 s48, v245, 45
	v_readlane_b32 s49, v245, 46
	s_nop 1
	v_cndmask_b32_e64 v28, v28, v218, s[48:49]
	v_readlane_b32 s48, v245, 47
	v_readlane_b32 s49, v245, 48
	s_nop 1
	v_cndmask_b32_e64 v12, v12, v218, s[48:49]
	v_readlane_b32 s48, v245, 49
	v_readlane_b32 s49, v245, 50
	s_nop 1
	v_cndmask_b32_e64 v29, v29, v218, s[48:49]
	v_readlane_b32 s48, v245, 51
	v_readlane_b32 s49, v245, 52
	s_nop 1
	v_cndmask_b32_e64 v13, v13, v218, s[48:49]
	v_readlane_b32 s48, v245, 53
	v_readlane_b32 s49, v245, 54
	s_nop 1
	v_cndmask_b32_e64 v30, v30, v218, s[48:49]
	v_readlane_b32 s48, v245, 55
	v_readlane_b32 s49, v245, 56
	s_nop 1
	v_cndmask_b32_e64 v14, v14, v218, s[48:49]
	v_readlane_b32 s48, v245, 57
	v_readlane_b32 s49, v245, 58
	s_nop 1
	v_cndmask_b32_e64 v31, v31, v218, s[48:49]
	v_readlane_b32 s48, v245, 59
	v_readlane_b32 s49, v245, 60
	s_nop 1
	v_cndmask_b32_e64 v15, v15, v218, s[48:49]
